# HGRN consumer waves also touch the K/Q/V lines of stages 2-4 at item start (cold-start prefetch)
# baseline (speedup 1.0000x reference)
.LBB0_146:
	v_mov_b32_e32 v36, v188
	s_nop 0
	v_readfirstlane_b32 s0, v36
	s_ashr_i32 s12, s0, 6
	s_and_b32 s1, s3, 0x70
	s_and_b32 s14, s3, 7
	s_lshl_b32 s14, s14, 1
	s_or_b32 s1, s1, s14
	s_bfe_u32 s14, s3, 0x10003
	s_or_b32 s1, s1, s14
	s_lshl_b32 s0, s1, 6
	s_and_b32 s11, s0, 0x780
	s_and_b32 s10, s0, 64
	s_cmp_lt_u32 s1, 64
	s_cselect_b64 s[36:37], -1, 0
	s_lshl_b32 s0, s1, 8
	s_and_b32 s4, s0, 0x2000
	v_and_b32_e32 v110, 15, v36
	v_lshrrev_b32_e32 v104, 4, v36
	v_bfe_u32 v106, v36, 4, 2
	s_cmp_lt_i32 s12, 4
	s_mov_b64 s[0:1], -1
	s_cbranch_scc0 .LBB0_153
	s_and_b64 s[14:15], s[36:37], exec
	s_cselect_b32 s1, 0, 0x4000000
	s_add_u32 s1, s88, s1
	s_addc_u32 s13, s89, 0
	s_lshl_b32 s14, s11, 1
	s_add_u32 s1, s1, s14
	s_addc_u32 s13, s13, 0
	s_lshl_b32 s14, s10, 1
	s_add_u32 s1, s1, s14
	s_addc_u32 s13, s13, 0
	s_lshl_b32 s14, s12, 4
	s_ashr_i32 s15, s14, 31
	s_lshl_b64 s[14:15], s[14:15], 1
	s_waitcnt lgkmcnt(0)
	v_lshlrev_b32_e32 v2, 3, v106
	s_add_u32 s14, s1, s14
	s_movk_i32 s1, 0x90
	v_mad_u32_u24 v3, v110, s1, v2
	v_readlane_b32 s1, v247, 63
	s_mulk_i32 s12, 0x900
	s_addc_u32 s15, s13, s15
	v_add_u32_e32 v40, s1, v3
	s_add_i32 s1, s12, 0
	v_cmp_gt_u32_e32 vcc, 2, v106
	s_add_i32 s1, s1, 0xd000
	v_add_u32_e32 v41, s1, v3
	v_cndmask_b32_e64 v0, v195, 0, vcc
	s_movk_i32 s1, 0x110
	v_lshlrev_b32_e32 v1, 3, v104
	v_lshlrev_b32_e32 v96, 1, v110
	v_mad_u32_u24 v0, v110, s1, v0
	v_lshl_add_u64 v[32:33], s[14:15], 0, v[96:97]
	v_mul_u32_u24_e32 v3, 0x110, v110
	v_and_or_b32 v0, v1, 8, v0
	v_readlane_b32 s1, v248, 0
	v_mov_b32_e32 v96, v97
	v_lshlrev_b32_e32 v37, 2, v106
	v_add_u32_e32 v42, s1, v0
	v_add3_u32 v43, v3, v2, 0
	v_mov_b32_e32 v98, v97
	s_waitcnt vmcnt(0)
	v_mov_b32_e32 v99, v97
	v_mov_b64_e32 v[0:1], v[96:97]
	v_mov_b64_e32 v[4:5], v[96:97]
	v_mov_b64_e32 v[8:9], v[96:97]
	v_mov_b64_e32 v[12:13], v[96:97]
	v_mov_b64_e32 v[16:17], v[96:97]
	v_mov_b64_e32 v[20:21], v[96:97]
	v_mov_b64_e32 v[24:25], v[96:97]
	v_mov_b64_e32 v[28:29], v[96:97]
	v_mov_b64_e32 v[2:3], v[98:99]
	v_mov_b64_e32 v[6:7], v[98:99]
	v_mov_b64_e32 v[10:11], v[98:99]
	v_mov_b64_e32 v[14:15], v[98:99]
	v_mov_b64_e32 v[18:19], v[98:99]
	v_mov_b64_e32 v[22:23], v[98:99]
	v_mov_b64_e32 v[26:27], v[98:99]
	v_mov_b64_e32 v[30:31], v[98:99]
	v_lshl_add_u32 v38, v106, 4, s73
	v_xor_b32_e32 v39, 0x203c, v37
	s_lshl_b32 s1, s4, 12
	s_add_u32 s14, s14, s1
	s_addc_u32 s15, s15, 0
	s_mov_b32 s13, 0x10000
	s_cmp_lg_u64 s[36:37], 0
	s_cselect_b32 s13, s13, 0xffff0000
	s_ashr_i32 s1, s13, 4
	v_add_u32_e32 v58, 0xffffffc3, v39
	v_cndmask_b32_e64 v58, v58, v37, s[36:37]
	v_lshlrev_b32_e32 v58, 12, v58
	v_lshl_add_u32 v160, v110, 1, v58
	v_add_u32_e32 v161, s1, v160
	v_add_u32_e32 v162, s1, v161
	v_add_u32_e32 v163, s1, v162
	s_lshl_b32 s1, s11, 1
	s_add_u32 s16, s76, s1
	s_addc_u32 s17, s77, 0
	s_lshl_b32 s18, s13, 2
	v_and_b32_e32 v169, 63, v36
	v_lshrrev_b32_e32 v170, 6, v36
	v_lshlrev_b32_e32 v170, 4, v170
	v_bfe_u32 v171, v169, 1, 4
	v_add_u32_e32 v171, v170, v171
	v_and_b32_e32 v172, 15, v169
	v_add_u32_e32 v172, v170, v172
	v_sub_u32_e32 v170, 0x1fff, v171
	v_cndmask_b32_e64 v171, v170, v171, s[36:37]
	v_sub_u32_e32 v170, 0x1fff, v172
	v_cndmask_b32_e64 v172, v170, v172, s[36:37]
	v_add_u32_e32 v171, s4, v171
	v_add_u32_e32 v172, s4, v172
	v_lshlrev_b32_e32 v171, 12, v171
	v_lshlrev_b32_e32 v172, 12, v172
	v_and_b32_e32 v170, 1, v169
	v_lshl_or_b32 v171, v170, 7, v171
	s_mov_b32 s1, 0x8000000
	s_cmp_lg_u64 s[36:37], 0
	s_cselect_b32 s1, s1, 0xc000000
	v_mov_b32_e32 v170, s1
	v_cmp_gt_u32_e32 vcc, 32, v169
	s_nop 1
	v_cndmask_b32_e32 v170, 0, v170, vcc
	v_add_u32_e32 v171, v170, v171
	s_lshl_b32 s1, s10, 1
	s_add_u32 s1, s1, 0x4000000
	v_add_u32_e32 v172, s1, v172
	s_lshl_b32 s1, s18, 1
	v_add_u32_e32 v171, s1, v171
	v_add_u32_e32 v172, s1, v172
	global_load_dword v167, v171, s[16:17]
	global_load_dword v168, v172, s[16:17]
	v_add_u32_e32 v171, s18, v171
	v_add_u32_e32 v172, s18, v172
	global_load_dword v167, v171, s[16:17]
	global_load_dword v168, v172, s[16:17]
	v_add_u32_e32 v171, s18, v171
	v_add_u32_e32 v172, s18, v172
	global_load_dword v167, v171, s[16:17]
	global_load_dword v168, v172, s[16:17]
	v_add_u32_e32 v171, s18, v171
	v_add_u32_e32 v172, s18, v172
	s_mov_b32 s0, 1
	s_barrier
